# MLA loop: user priority steps down 3-2-1-0 with a wave's progress through the tile iteration, so the SIMD partner that is behind wins arbitration (measured 25% barrier wait on the leading wave before)
# baseline (speedup 1.0000x reference)
.Lmla_loop:
.Lmla_it0:
	s_add_i32 s42, s65, 3
	s_min_u32 s42, s42, s44
	s_lshl_b64 s[6:7], s[42:43], 17
	v_lshl_add_u64 v[242:243], v[190:191], 0, s[6:7]
	s_lshl_b64 s[6:7], s[42:43], 12
	v_lshl_add_u64 v[244:245], v[194:195], 0, s[6:7]
	s_add_i32 s42, s65, 2
	s_min_u32 s42, s42, s44
	s_lshl_b64 s[6:7], s[42:43], 17
	v_lshl_add_u64 v[246:247], v[192:193], 0, s[6:7]
	global_load_dwordx4 v[6:9], v[242:243], off
	global_load_dwordx4 v[10:13], v[246:247], off
	global_load_dwordx4 v[2:5], v[244:245], off
	s_cmp_ge_u32 s65, s45
	s_cbranch_scc1 .Lmla_skip0
	s_add_i32 s41, s65, 1
	s_cmp_ge_u32 s41, s64
	s_cselect_b32 s7, 1, 0
	s_cmp_lt_u32 s41, s45
	s_cselect_b32 s26, 1, 0
	s_and_b32 s56, s7, s26
	s_lshl_b32 s27, s41, 6
	ds_read_b128 v[164:167], v210 offset:25600
	ds_read_b128 v[168:171], v210 offset:25632
	ds_read_b128 v[172:175], v210 offset:25664
	ds_read_b128 v[214:217], v210 offset:25696
	ds_read_b128 v[218:221], v210 offset:25728
	ds_read_b128 v[222:225], v210 offset:25760
	s_setprio 3
	v_exp_f32_e32 v64, v64
	v_exp_f32_e32 v65, v65
	v_exp_f32_e32 v66, v66
	v_exp_f32_e32 v67, v67
	s_waitcnt lgkmcnt(5)
	v_mfma_f32_32x32x16_bf16 v[132:147], v[164:167], v[96:99], v[48:63]
	ds_read_b128 v[164:167], v210 offset:32256
	v_add_f32_e32 v14, v64, v65
	v_add_f32_e32 v15, v66, v67
	v_exp_f32_e32 v68, v68
	v_exp_f32_e32 v69, v69
	s_waitcnt lgkmcnt(5)
	v_mfma_f32_32x32x16_bf16 v[132:147], v[168:171], v[100:103], v[132:147]
	ds_read_b128 v[168:171], v210 offset:32288
	v_exp_f32_e32 v70, v70
	v_exp_f32_e32 v71, v71
	v_add_f32_e32 v14, v14, v15
	v_add_f32_e32 v15, v68, v69
	s_waitcnt lgkmcnt(5)
	v_mfma_f32_32x32x16_bf16 v[132:147], v[172:175], v[104:107], v[132:147]
	ds_read_b128 v[172:175], v210 offset:32320
	v_add_f32_e32 v213, v70, v71
	v_cvt_pk_bf16_f32 v64, v64, v65
	v_cvt_pk_bf16_f32 v65, v66, v67
	v_cvt_pk_bf16_f32 v66, v68, v69
	v_cvt_pk_bf16_f32 v67, v70, v71
	s_waitcnt lgkmcnt(5)
	v_mfma_f32_32x32x16_bf16 v[132:147], v[214:217], v[108:111], v[132:147]
	ds_read_b128 v[214:217], v210 offset:32352
	v_exp_f32_e32 v72, v72
	v_exp_f32_e32 v73, v73
	v_exp_f32_e32 v74, v74
	v_exp_f32_e32 v75, v75
	s_waitcnt lgkmcnt(5)
	v_mfma_f32_32x32x16_bf16 v[132:147], v[218:221], v[112:115], v[132:147]
	ds_read_b128 v[218:221], v210 offset:32384
	v_add_f32_e32 v14, v14, v15
	v_add_f32_e32 v14, v14, v213
	v_exp_f32_e32 v76, v76
	v_exp_f32_e32 v77, v77
	s_setprio 2
	s_waitcnt lgkmcnt(5)
	v_mfma_f32_32x32x16_bf16 v[132:147], v[222:225], v[116:119], v[132:147]
	ds_read_b128 v[222:225], v210 offset:32416
	v_exp_f32_e32 v78, v78
	v_exp_f32_e32 v79, v79
	v_add_f32_e32 v15, v72, v73
	v_add_f32_e32 v213, v74, v75
	s_waitcnt lgkmcnt(5)
	v_mfma_f32_32x32x16_bf16 v[148:163], v[164:167], v[96:99], v[48:63]
	ds_read_b64_tr_b16 v[226:227], v211 offset:13312
	ds_read_b64_tr_b16 v[228:229], v211 offset:14848
	v_add_f32_e32 v248, v76, v77
	v_add_f32_e32 v249, v78, v79
	v_cvt_pk_bf16_f32 v68, v72, v73
	v_cvt_pk_bf16_f32 v69, v74, v75
	v_cvt_pk_bf16_f32 v70, v76, v77
	v_cvt_pk_bf16_f32 v71, v78, v79
	s_waitcnt lgkmcnt(6)
	v_mfma_f32_32x32x16_bf16 v[148:163], v[168:171], v[100:103], v[148:163]
	ds_read_b64_tr_b16 v[230:231], v211 offset:13376
	ds_read_b64_tr_b16 v[232:233], v211 offset:14912
	v_add_f32_e32 v15, v15, v213
	v_add_f32_e32 v248, v248, v249
	v_exp_f32_e32 v80, v80
	v_exp_f32_e32 v81, v81
	s_waitcnt lgkmcnt(7)
	v_mfma_f32_32x32x16_bf16 v[148:163], v[172:175], v[104:107], v[148:163]
	ds_read_b64_tr_b16 v[234:235], v211 offset:16384
	ds_read_b64_tr_b16 v[236:237], v211 offset:17920
	v_exp_f32_e32 v82, v82
	v_exp_f32_e32 v83, v83
	v_add_f32_e32 v14, v14, v15
	v_add_f32_e32 v14, v14, v248
	s_waitcnt lgkmcnt(8)
	v_mfma_f32_32x32x16_bf16 v[148:163], v[214:217], v[108:111], v[148:163]
	ds_read_b64_tr_b16 v[238:239], v211 offset:16448
	ds_read_b64_tr_b16 v[240:241], v211 offset:17984
	v_add_f32_e32 v15, v80, v81
	v_add_f32_e32 v213, v82, v83
	v_exp_f32_e32 v84, v84
	v_exp_f32_e32 v85, v85
	s_setprio 1
	s_waitcnt lgkmcnt(9)
	v_mfma_f32_32x32x16_bf16 v[148:163], v[218:221], v[112:115], v[148:163]
	v_exp_f32_e32 v86, v86
	v_exp_f32_e32 v87, v87
	v_add_f32_e32 v15, v15, v213
	v_add_f32_e32 v213, v84, v85
	s_waitcnt lgkmcnt(8)
	v_mfma_f32_32x32x16_bf16 v[148:163], v[222:225], v[116:119], v[148:163]
	v_add_f32_e32 v248, v86, v87
	v_cvt_pk_bf16_f32 v80, v80, v81
	v_cvt_pk_bf16_f32 v81, v82, v83
	v_cvt_pk_bf16_f32 v82, v84, v85
	v_cvt_pk_bf16_f32 v83, v86, v87
	s_waitcnt lgkmcnt(6)
	v_mfma_f32_32x32x16_bf16 v[32:47], v[226:229], v[64:67], v[32:47]
	ds_read_b64_tr_b16 v[226:227], v211 offset:19456
	ds_read_b64_tr_b16 v[228:229], v211 offset:20992
	v_exp_f32_e32 v88, v88
	v_exp_f32_e32 v89, v89
	v_exp_f32_e32 v90, v90
	v_exp_f32_e32 v91, v91
	s_waitcnt lgkmcnt(6)
	v_mfma_f32_32x32x16_bf16 v[16:31], v[230:233], v[64:67], v[16:31]
	ds_read_b64_tr_b16 v[230:231], v211 offset:19520
	ds_read_b64_tr_b16 v[232:233], v211 offset:21056
	v_add_f32_e32 v213, v213, v248
	v_add_f32_e32 v15, v15, v213
	v_exp_f32_e32 v92, v92
	v_exp_f32_e32 v93, v93
	s_waitcnt lgkmcnt(6)
	v_mfma_f32_32x32x16_bf16 v[32:47], v[234:237], v[68:71], v[32:47]
	ds_read_b64_tr_b16 v[234:235], v211 offset:22528
	ds_read_b64_tr_b16 v[236:237], v211 offset:24064
	v_exp_f32_e32 v94, v94
	v_exp_f32_e32 v95, v95
	v_add_f32_e32 v213, v88, v89
	v_add_f32_e32 v248, v90, v91
	s_setprio 0
	s_waitcnt lgkmcnt(6)
	v_mfma_f32_32x32x16_bf16 v[16:31], v[238:241], v[68:71], v[16:31]
	ds_read_b64_tr_b16 v[238:239], v211 offset:22592
	ds_read_b64_tr_b16 v[240:241], v211 offset:24128
	s_cmp_lg_u32 s56, 0
	s_cbranch_scc1 .Lmla_mask0

.Lmla_end0:
.Lmla_it1:
	s_add_i32 s66, s65, 1
	s_add_i32 s42, s66, 3
	s_min_u32 s42, s42, s44
	s_lshl_b64 s[6:7], s[42:43], 17
	v_lshl_add_u64 v[242:243], v[190:191], 0, s[6:7]
	s_lshl_b64 s[6:7], s[42:43], 12
	v_lshl_add_u64 v[244:245], v[194:195], 0, s[6:7]
	s_add_i32 s42, s66, 2
	s_min_u32 s42, s42, s44
	s_lshl_b64 s[6:7], s[42:43], 17
	v_lshl_add_u64 v[246:247], v[192:193], 0, s[6:7]
	global_load_dwordx4 v[120:123], v[242:243], off
	global_load_dwordx4 v[124:127], v[246:247], off
	global_load_dwordx4 v[128:131], v[244:245], off
	s_cmp_ge_u32 s66, s45
	s_cbranch_scc1 .Lmla_skip1
	s_add_i32 s41, s66, 1
	s_cmp_ge_u32 s41, s64
	s_cselect_b32 s7, 1, 0
	s_cmp_lt_u32 s41, s45
	s_cselect_b32 s26, 1, 0
	s_and_b32 s56, s7, s26
	s_lshl_b32 s27, s41, 6
	ds_read_b128 v[164:167], v210 offset:0
	ds_read_b128 v[168:171], v210 offset:32
	ds_read_b128 v[172:175], v210 offset:64
	ds_read_b128 v[214:217], v210 offset:96
	ds_read_b128 v[218:221], v210 offset:128
	ds_read_b128 v[222:225], v210 offset:160
	s_setprio 3
	v_exp_f32_e32 v132, v132
	v_exp_f32_e32 v133, v133
	v_exp_f32_e32 v134, v134
	v_exp_f32_e32 v135, v135
	s_waitcnt lgkmcnt(5)
	v_mfma_f32_32x32x16_bf16 v[64:79], v[164:167], v[96:99], v[48:63]
	ds_read_b128 v[164:167], v210 offset:6656
	v_add_f32_e32 v14, v132, v133
	v_add_f32_e32 v15, v134, v135
	v_exp_f32_e32 v136, v136
	v_exp_f32_e32 v137, v137
	s_waitcnt lgkmcnt(5)
	v_mfma_f32_32x32x16_bf16 v[64:79], v[168:171], v[100:103], v[64:79]
	ds_read_b128 v[168:171], v210 offset:6688
	v_exp_f32_e32 v138, v138
	v_exp_f32_e32 v139, v139
	v_add_f32_e32 v14, v14, v15
	v_add_f32_e32 v15, v136, v137
	s_waitcnt lgkmcnt(5)
	v_mfma_f32_32x32x16_bf16 v[64:79], v[172:175], v[104:107], v[64:79]
	ds_read_b128 v[172:175], v210 offset:6720
	v_add_f32_e32 v213, v138, v139
	v_cvt_pk_bf16_f32 v132, v132, v133
	v_cvt_pk_bf16_f32 v133, v134, v135
	v_cvt_pk_bf16_f32 v134, v136, v137
	v_cvt_pk_bf16_f32 v135, v138, v139
	s_waitcnt lgkmcnt(5)
	v_mfma_f32_32x32x16_bf16 v[64:79], v[214:217], v[108:111], v[64:79]
	ds_read_b128 v[214:217], v210 offset:6752
	v_exp_f32_e32 v140, v140
	v_exp_f32_e32 v141, v141
	v_exp_f32_e32 v142, v142
	v_exp_f32_e32 v143, v143
	s_waitcnt lgkmcnt(5)
	v_mfma_f32_32x32x16_bf16 v[64:79], v[218:221], v[112:115], v[64:79]
	ds_read_b128 v[218:221], v210 offset:6784
	v_add_f32_e32 v14, v14, v15
	v_add_f32_e32 v14, v14, v213
	v_exp_f32_e32 v144, v144
	v_exp_f32_e32 v145, v145
	s_setprio 2
	s_waitcnt lgkmcnt(5)
	v_mfma_f32_32x32x16_bf16 v[64:79], v[222:225], v[116:119], v[64:79]
	ds_read_b128 v[222:225], v210 offset:6816
	v_exp_f32_e32 v146, v146
	v_exp_f32_e32 v147, v147
	v_add_f32_e32 v15, v140, v141
	v_add_f32_e32 v213, v142, v143
	s_waitcnt lgkmcnt(5)
	v_mfma_f32_32x32x16_bf16 v[80:95], v[164:167], v[96:99], v[48:63]
	ds_read_b64_tr_b16 v[226:227], v211 offset:38912
	ds_read_b64_tr_b16 v[228:229], v211 offset:40448
	v_add_f32_e32 v248, v144, v145
	v_add_f32_e32 v249, v146, v147
	v_cvt_pk_bf16_f32 v136, v140, v141
	v_cvt_pk_bf16_f32 v137, v142, v143
	v_cvt_pk_bf16_f32 v138, v144, v145
	v_cvt_pk_bf16_f32 v139, v146, v147
	s_waitcnt lgkmcnt(6)
	v_mfma_f32_32x32x16_bf16 v[80:95], v[168:171], v[100:103], v[80:95]
	ds_read_b64_tr_b16 v[230:231], v211 offset:38976
	ds_read_b64_tr_b16 v[232:233], v211 offset:40512
	v_add_f32_e32 v15, v15, v213
	v_add_f32_e32 v248, v248, v249
	v_exp_f32_e32 v148, v148
	v_exp_f32_e32 v149, v149
	s_waitcnt lgkmcnt(7)
	v_mfma_f32_32x32x16_bf16 v[80:95], v[172:175], v[104:107], v[80:95]
	ds_read_b64_tr_b16 v[234:235], v211 offset:41984
	ds_read_b64_tr_b16 v[236:237], v211 offset:43520
	v_exp_f32_e32 v150, v150
	v_exp_f32_e32 v151, v151
	v_add_f32_e32 v14, v14, v15
	v_add_f32_e32 v14, v14, v248
	s_waitcnt lgkmcnt(8)
	v_mfma_f32_32x32x16_bf16 v[80:95], v[214:217], v[108:111], v[80:95]
	ds_read_b64_tr_b16 v[238:239], v211 offset:42048
	ds_read_b64_tr_b16 v[240:241], v211 offset:43584
	v_add_f32_e32 v15, v148, v149
	v_add_f32_e32 v213, v150, v151
	v_exp_f32_e32 v152, v152
	v_exp_f32_e32 v153, v153
	s_setprio 1
	s_waitcnt lgkmcnt(9)
	v_mfma_f32_32x32x16_bf16 v[80:95], v[218:221], v[112:115], v[80:95]
	v_exp_f32_e32 v154, v154
	v_exp_f32_e32 v155, v155
	v_add_f32_e32 v15, v15, v213
	v_add_f32_e32 v213, v152, v153
	s_waitcnt lgkmcnt(8)
	v_mfma_f32_32x32x16_bf16 v[80:95], v[222:225], v[116:119], v[80:95]
	v_add_f32_e32 v248, v154, v155
	v_cvt_pk_bf16_f32 v148, v148, v149
	v_cvt_pk_bf16_f32 v149, v150, v151
	v_cvt_pk_bf16_f32 v150, v152, v153
	v_cvt_pk_bf16_f32 v151, v154, v155
	s_waitcnt lgkmcnt(6)
	v_mfma_f32_32x32x16_bf16 v[32:47], v[226:229], v[132:135], v[32:47]
	ds_read_b64_tr_b16 v[226:227], v211 offset:45056
	ds_read_b64_tr_b16 v[228:229], v211 offset:46592
	v_exp_f32_e32 v156, v156
	v_exp_f32_e32 v157, v157
	v_exp_f32_e32 v158, v158
	v_exp_f32_e32 v159, v159
	s_waitcnt lgkmcnt(6)
	v_mfma_f32_32x32x16_bf16 v[16:31], v[230:233], v[132:135], v[16:31]
	ds_read_b64_tr_b16 v[230:231], v211 offset:45120
	ds_read_b64_tr_b16 v[232:233], v211 offset:46656
	v_add_f32_e32 v213, v213, v248
	v_add_f32_e32 v15, v15, v213
	v_exp_f32_e32 v160, v160
	v_exp_f32_e32 v161, v161
	s_waitcnt lgkmcnt(6)
	v_mfma_f32_32x32x16_bf16 v[32:47], v[234:237], v[136:139], v[32:47]
	ds_read_b64_tr_b16 v[234:235], v211 offset:48128
	ds_read_b64_tr_b16 v[236:237], v211 offset:49664
	v_exp_f32_e32 v162, v162
	v_exp_f32_e32 v163, v163
	v_add_f32_e32 v213, v156, v157
	v_add_f32_e32 v248, v158, v159
	s_setprio 0
	s_waitcnt lgkmcnt(6)
	v_mfma_f32_32x32x16_bf16 v[16:31], v[238:241], v[136:139], v[16:31]
	ds_read_b64_tr_b16 v[238:239], v211 offset:48192
	ds_read_b64_tr_b16 v[240:241], v211 offset:49728
	s_cmp_lg_u32 s56, 0
	s_cbranch_scc1 .Lmla_mask1
